# fourier output step rewritten (digit arithmetic for the mirrored bin, 8 LDS reads in flight) on top of v21
# speedup vs baseline: 1.0163x; 1.0003x over previous
; #define GAS __attribute__((address_space(1)))
; #define LAS __attribute__((address_space(3)))
; __device__ __forceinline__ int freq_pos(int k) { return phys(((k & 15) << 10) | (((k >> 4) & 15) << 6) | (((k >> 8) & 15) << 2) | (k >> 12)); }
; #define LT() ({ int lt_ = tid; asm volatile("" : "+v"(lt_)); lt_; })
; template <bool INV> __device__ __forceinline__ void pass4_s1(LAS f32x2* X, int b) {
;     LAS f32x4* P = (LAS f32x4*)(X + 4 * b + ((b >> 4) << 2));
;     const f32x4 u = P[0], v = P[1];
;     f32x2 x0 = {u.x, u.y}, x1 = {u.z, u.w}, x2 = {v.x, v.y}, x3 = {v.z, v.w};
;     r4<INV>(x0, x1, x2, x3);
;     P[0] = (f32x4){x0.x, x0.y, x1.x, x1.y}; P[1] = (f32x4){x2.x, x2.y, x3.x, x3.y};
; }
; __device__ __forceinline__ void fourier_latent(Frame& F, int b, int gq, int m, LAS f32x2* X, const LAS f32x2* TH, const LAS f32x2* TL, bool wr = true) {
;     ...
;     const float sc = 6.9053396600248786e-4f;
; #pragma unroll 2
;     for (int i = 0; i < 8; ++i) { const int g = LT() + NTHR * i, k0 = 4 * g; f32x4 oa, ob;
; #pragma unroll
;         for (int e = 0; e < 4; ++e) { const int k = k0 + e; const f32x2 u = X[freq_pos(k)], v = X[freq_pos((FFTN - k) & (FFTN - 1))];
;             if (m != 0) { oa[e] = u.x * sc; ob[e] = v.x * sc; } else { oa[e] = (u.x + v.x) * (0.5f * sc); ob[e] = (u.y + v.y) * (0.5f * sc); } }
;         if (wr) { *(GAS f32x4*)(ra + k0) = oa; *(GAS f32x4*)(rb + k0) = ob; } }
.LBB0_950:
	v_add_lshl_u32 v1, v140, s0, 1
	v_and_b32_e32 v2, 0xffffffe0, v1
	v_add_u32_e32 v14, v0, v2
	ds_read_b128 v[2:5], v14
	ds_read_b128 v[6:9], v14 offset:16
	v_add_u32_e32 v1, 0x400, v1
	v_and_b32_e32 v1, 0xffffffe0, v1
	v_add_u32_e32 v1, v0, v1
	s_addk_i32 s0, 0x400
	s_waitcnt lgkmcnt(0)
	v_pk_add_f32 v[10:11], v[2:3], v[6:7]
	v_pk_add_f32 v[12:13], v[2:3], v[6:7] neg_lo:[0,1] neg_hi:[0,1]
	v_pk_add_f32 v[2:3], v[4:5], v[8:9] neg_lo:[0,1] neg_hi:[0,1]
	v_pk_add_f32 v[6:7], v[4:5], v[8:9]
	v_xor_b32_e32 v9, 0x80000000, v2
	v_mov_b32_e32 v8, v3
	v_pk_add_f32 v[2:3], v[10:11], v[6:7]
	v_pk_add_f32 v[4:5], v[12:13], v[8:9]
	v_pk_add_f32 v[6:7], v[10:11], v[6:7] neg_lo:[0,1] neg_hi:[0,1]
	v_pk_add_f32 v[8:9], v[12:13], v[8:9] neg_lo:[0,1] neg_hi:[0,1]
	ds_write_b128 v14, v[2:5]
	ds_write_b128 v14, v[6:9] offset:16
	ds_read_b128 v[2:5], v1 offset:16384
	ds_read_b128 v[6:9], v1 offset:16400
	s_cmpk_lg_i32 s0, 0x1000
	v_add_u32_e32 v0, 0x8000, v0
	s_waitcnt lgkmcnt(0)
	v_pk_add_f32 v[10:11], v[2:3], v[6:7]
	v_pk_add_f32 v[12:13], v[2:3], v[6:7] neg_lo:[0,1] neg_hi:[0,1]
	v_pk_add_f32 v[2:3], v[4:5], v[8:9] neg_lo:[0,1] neg_hi:[0,1]
	v_pk_add_f32 v[6:7], v[4:5], v[8:9]
	v_xor_b32_e32 v9, 0x80000000, v2
	v_mov_b32_e32 v8, v3
	v_pk_add_f32 v[2:3], v[10:11], v[6:7]
	v_pk_add_f32 v[4:5], v[12:13], v[8:9]
	v_pk_add_f32 v[6:7], v[10:11], v[6:7] neg_lo:[0,1] neg_hi:[0,1]
	v_pk_add_f32 v[8:9], v[12:13], v[8:9] neg_lo:[0,1] neg_hi:[0,1]
	ds_write_b128 v1, v[2:5] offset:16384
	ds_write_b128 v1, v[6:9] offset:16400
	s_cbranch_scc1 .LBB0_950
	s_waitcnt lgkmcnt(0)
	s_barrier
	s_cmp_lg_u32 s5, 0
	s_cselect_b32 s14, 1, 0
	v_lshlrev_b32_e32 v40, 4, v140
	v_lshlrev_b32_e32 v41, 2, v140
	s_movk_i32 s0, 0x2200
	s_movk_i32 s2, 0x220
	s_mov_b32 s3, 0
.Lfo_loop:
	v_and_b32_e32 v0, 15, v41
	v_bfe_u32 v1, v41, 4, 4
	v_bfe_u32 v2, v41, 8, 4
	v_lshrrev_b32_e32 v3, 12, v41
	v_lshlrev_b32_e32 v3, 3, v3
	v_lshl_add_u32 v2, v2, 5, v3
	v_mad_u32_u24 v1, v1, s2, v2
	v_mad_u32_u24 v0, v0, s0, v1
	ds_read_b64 v[4:5], v0
	ds_read_b64 v[6:7], v0 offset:8704
	ds_read_b64 v[8:9], v0 offset:17408
	ds_read_b64 v[10:11], v0 offset:26112
	v_sub_u32_e32 v12, 0x4000, v41
	v_and_b32_e32 v13, 0x3fff, v12
	v_and_b32_e32 v14, 15, v13
	v_bfe_u32 v1, v13, 4, 4
	v_bfe_u32 v2, v13, 8, 4
	v_lshrrev_b32_e32 v3, 12, v13
	v_lshlrev_b32_e32 v3, 3, v3
	v_lshl_add_u32 v2, v2, 5, v3
	v_mad_u32_u24 v1, v1, s2, v2
	v_mad_u32_u24 v14, v14, s0, v1
	ds_read_b64 v[28:29], v14
	v_add_u32_e32 v13, -1, v12
	v_and_b32_e32 v13, 0x3fff, v13
	v_and_b32_e32 v15, 15, v13
	v_bfe_u32 v1, v13, 4, 4
	v_bfe_u32 v2, v13, 8, 4
	v_lshrrev_b32_e32 v3, 12, v13
	v_lshlrev_b32_e32 v3, 3, v3
	v_lshl_add_u32 v2, v2, 5, v3
	v_mad_u32_u24 v1, v1, s2, v2
	v_mad_u32_u24 v15, v15, s0, v1
	ds_read_b64 v[30:31], v15
	v_add_u32_e32 v13, -2, v12
	v_and_b32_e32 v13, 0x3fff, v13
	v_and_b32_e32 v16, 15, v13
	v_bfe_u32 v1, v13, 4, 4
	v_bfe_u32 v2, v13, 8, 4
	v_lshrrev_b32_e32 v3, 12, v13
	v_lshlrev_b32_e32 v3, 3, v3
	v_lshl_add_u32 v2, v2, 5, v3
	v_mad_u32_u24 v1, v1, s2, v2
	v_mad_u32_u24 v16, v16, s0, v1
	ds_read_b64 v[32:33], v16
	v_add_u32_e32 v13, -3, v12
	v_and_b32_e32 v13, 0x3fff, v13
	v_and_b32_e32 v18, 15, v13
	v_bfe_u32 v1, v13, 4, 4
	v_bfe_u32 v2, v13, 8, 4
	v_lshrrev_b32_e32 v3, 12, v13
	v_lshlrev_b32_e32 v3, 3, v3
	v_lshl_add_u32 v2, v2, 5, v3
	v_mad_u32_u24 v1, v1, s2, v2
	v_mad_u32_u24 v18, v18, s0, v1
	ds_read_b64 v[34:35], v18
	v_add_u32_e32 v41, 0x800, v41
	s_add_i32 s3, s3, 1
	s_cmp_eq_u32 s14, 0
	s_waitcnt lgkmcnt(0)
	s_cbranch_scc1 .Lfo_m0
	v_mul_f32_e32 v20, 0x3a3504f3, v4
	v_mul_f32_e32 v21, 0x3a3504f3, v6
	v_mul_f32_e32 v22, 0x3a3504f3, v8
	v_mul_f32_e32 v23, 0x3a3504f3, v10
	v_mul_f32_e32 v24, 0x3a3504f3, v28
	v_mul_f32_e32 v25, 0x3a3504f3, v30
	v_mul_f32_e32 v26, 0x3a3504f3, v32
	v_mul_f32_e32 v27, 0x3a3504f3, v34
	s_branch .Lfo_st
.Lfo_m0:
	v_pk_add_f32 v[4:5], v[4:5], v[28:29]
	v_pk_add_f32 v[6:7], v[6:7], v[30:31]
	v_pk_add_f32 v[8:9], v[8:9], v[32:33]
	v_pk_add_f32 v[10:11], v[10:11], v[34:35]
	v_mul_f32_e32 v20, 0x39b504f3, v4
	v_mul_f32_e32 v21, 0x39b504f3, v6
	v_mul_f32_e32 v22, 0x39b504f3, v8
	v_mul_f32_e32 v23, 0x39b504f3, v10
	v_mul_f32_e32 v24, 0x39b504f3, v5
	v_mul_f32_e32 v25, 0x39b504f3, v7
	v_mul_f32_e32 v26, 0x39b504f3, v9
	v_mul_f32_e32 v27, 0x39b504f3, v11
.Lfo_st:
	s_nop 0
	global_store_dwordx4 v40, v[20:23], s[10:11]
	global_store_dwordx4 v40, v[24:27], s[12:13]
	s_cmp_lg_u32 s3, 8
	v_add_u32_e32 v40, 0x2000, v40
	s_cbranch_scc1 .Lfo_loop
	s_branch .LBB0_942
